# P0: compress-bias dot product (waves 0-511) loads batched 16 deep instead of one serialized round trip per element
# baseline (speedup 1.0000x reference)
.LBB0_28:
	s_and_b32 s0, s13, 0xff
	s_lshl_b32 s4, s0, 2
	s_cmpk_lt_i32 s21, 0x100
	s_cselect_b64 s[14:15], -1, 0
	s_and_b64 s[0:1], s[14:15], exec
	s_waitcnt lgkmcnt(0)
	s_cselect_b32 s17, s49, s55
	s_cselect_b32 s16, s48, s54
	s_cselect_b32 s1, s47, s53
	s_cselect_b32 s0, s46, s52
	v_lshl_add_u64 v[8:9], s[16:17], 0, v[4:5]
	v_lshl_add_u64 v[6:7], s[0:1], 0, v[2:3]
	v_lshl_add_u64 v[8:9], v[8:9], 0, s[4:5]
	s_movk_i32 s0, 4
	s_mov_b64 s[16:17], 0x1000
	v_mov_b32_e32 v16, 0
.Lbias_batch:
	global_load_dword v20, v[6:7], off
	global_load_dword v36, v[8:9], off
	v_lshl_add_u64 v[8:9], v[8:9], 0, s[8:9]
	global_load_dword v21, v[6:7], off offset:256
	global_load_dword v37, v[8:9], off
	v_lshl_add_u64 v[8:9], v[8:9], 0, s[8:9]
	global_load_dword v22, v[6:7], off offset:512
	global_load_dword v38, v[8:9], off
	v_lshl_add_u64 v[8:9], v[8:9], 0, s[8:9]
	global_load_dword v23, v[6:7], off offset:768
	global_load_dword v39, v[8:9], off
	v_lshl_add_u64 v[8:9], v[8:9], 0, s[8:9]
	global_load_dword v24, v[6:7], off offset:1024
	global_load_dword v40, v[8:9], off
	v_lshl_add_u64 v[8:9], v[8:9], 0, s[8:9]
	global_load_dword v25, v[6:7], off offset:1280
	global_load_dword v41, v[8:9], off
	v_lshl_add_u64 v[8:9], v[8:9], 0, s[8:9]
	global_load_dword v26, v[6:7], off offset:1536
	global_load_dword v42, v[8:9], off
	v_lshl_add_u64 v[8:9], v[8:9], 0, s[8:9]
	global_load_dword v27, v[6:7], off offset:1792
	global_load_dword v43, v[8:9], off
	v_lshl_add_u64 v[8:9], v[8:9], 0, s[8:9]
	global_load_dword v28, v[6:7], off offset:2048
	global_load_dword v44, v[8:9], off
	v_lshl_add_u64 v[8:9], v[8:9], 0, s[8:9]
	global_load_dword v29, v[6:7], off offset:2304
	global_load_dword v45, v[8:9], off
	v_lshl_add_u64 v[8:9], v[8:9], 0, s[8:9]
	global_load_dword v30, v[6:7], off offset:2560
	global_load_dword v46, v[8:9], off
	v_lshl_add_u64 v[8:9], v[8:9], 0, s[8:9]
	global_load_dword v31, v[6:7], off offset:2816
	global_load_dword v47, v[8:9], off
	v_lshl_add_u64 v[8:9], v[8:9], 0, s[8:9]
	global_load_dword v32, v[6:7], off offset:3072
	global_load_dword v48, v[8:9], off
	v_lshl_add_u64 v[8:9], v[8:9], 0, s[8:9]
	global_load_dword v33, v[6:7], off offset:3328
	global_load_dword v49, v[8:9], off
	v_lshl_add_u64 v[8:9], v[8:9], 0, s[8:9]
	global_load_dword v34, v[6:7], off offset:3584
	global_load_dword v50, v[8:9], off
	v_lshl_add_u64 v[8:9], v[8:9], 0, s[8:9]
	global_load_dword v35, v[6:7], off offset:3840
	global_load_dword v51, v[8:9], off
	v_lshl_add_u64 v[8:9], v[8:9], 0, s[8:9]
	v_lshl_add_u64 v[6:7], v[6:7], 0, s[16:17]
	s_waitcnt vmcnt(30)
	v_fmac_f32_e32 v16, v20, v36
	s_waitcnt vmcnt(28)
	v_fmac_f32_e32 v16, v21, v37
	s_waitcnt vmcnt(26)
	v_fmac_f32_e32 v16, v22, v38
	s_waitcnt vmcnt(24)
	v_fmac_f32_e32 v16, v23, v39
	s_waitcnt vmcnt(22)
	v_fmac_f32_e32 v16, v24, v40
	s_waitcnt vmcnt(20)
	v_fmac_f32_e32 v16, v25, v41
	s_waitcnt vmcnt(18)
	v_fmac_f32_e32 v16, v26, v42
	s_waitcnt vmcnt(16)
	v_fmac_f32_e32 v16, v27, v43
	s_waitcnt vmcnt(14)
	v_fmac_f32_e32 v16, v28, v44
	s_waitcnt vmcnt(12)
	v_fmac_f32_e32 v16, v29, v45
	s_waitcnt vmcnt(10)
	v_fmac_f32_e32 v16, v30, v46
	s_waitcnt vmcnt(8)
	v_fmac_f32_e32 v16, v31, v47
	s_waitcnt vmcnt(6)
	v_fmac_f32_e32 v16, v32, v48
	s_waitcnt vmcnt(4)
	v_fmac_f32_e32 v16, v33, v49
	s_waitcnt vmcnt(2)
	v_fmac_f32_e32 v16, v34, v50
	s_waitcnt vmcnt(0)
	v_fmac_f32_e32 v16, v35, v51
	s_sub_i32 s0, s0, 1
	s_cmp_lg_u32 s0, 0
	s_cbranch_scc1 .Lbias_batch
	ds_bpermute_b32 v6, v1, v16
	s_waitcnt lgkmcnt(0)
	v_add_f32_e32 v6, v16, v6
	ds_bpermute_b32 v7, v10, v6
	s_waitcnt lgkmcnt(0)
	v_add_f32_e32 v6, v6, v7
	ds_bpermute_b32 v7, v11, v6
	s_waitcnt lgkmcnt(0)
	v_add_f32_e32 v6, v6, v7
	ds_bpermute_b32 v7, v12, v6
	s_waitcnt lgkmcnt(0)
	v_add_f32_e32 v6, v6, v7
	ds_bpermute_b32 v7, v13, v6
	s_waitcnt lgkmcnt(0)
	v_add_f32_e32 v6, v6, v7
	ds_bpermute_b32 v7, v14, v6
	s_and_saveexec_b64 s[0:1], vcc
	s_cbranch_execz .LBB0_27
	s_and_b32 s4, s21, 0xff
	s_and_b64 s[14:15], s[14:15], exec
	s_cselect_b32 s14, s20, 0xc0400
	s_add_u32 s14, s72, s14
	s_addc_u32 s15, s73, 0
	s_lshl_b32 s4, s4, 2
	s_waitcnt lgkmcnt(0)
	v_add_f32_e32 v6, v6, v7
	v_mov_b32_e32 v7, s4
	global_store_dword v7, v6, s[14:15]
	s_branch .LBB0_27
